# pool window sums: rolling LDS read pipeline (2-4 reads always in flight)
# speedup vs baseline: 1.0006x; 1.0006x over previous
; #define LAS __attribute__((address_space(3)))
; __device__ __forceinline__ void mix_phase(LAS unsigned char* lds, const Params& p, const int layer) {
;     ...
; #pragma unroll
;             for (int i = 0; i < 2; ++i) {
;                 const int rl = (tid >> 5) + 16 * i, bi = prt ? rl + 15 : (rl >> 3) * 23 + 15 + (rl & 7), t = (r0 + rl) & 2047;
;                 const LAS float* sp = SL + bi * 264 + q * 8;
;                 const f32x4 u0 = *(const LAS f32x4*)sp, u1 = *(const LAS f32x4*)(sp + 4);
;                 f32x4 s0 = u0, s1 = u1;
; #pragma unroll 4
;                 for (int j = 1; j < w; ++j) { s0 += *(const LAS f32x4*)(sp - j * 264); s1 += *(const LAS f32x4*)(sp - j * 264 + 4); }
;                 const int cnt = (prt && t + 1 < w) ? t + 1 : w; const float inv = 1.0f / (float)cnt;
.LBB0_585:
	s_lshl_b32 s13, 2, s12
	s_add_i32 s14, s13, -1
	v_lshl_add_u32 v0, v121, 1, s7
	v_and_b32_e32 v0, 0x7ff, v0
	v_add_u32_e32 v0, 1, v0
	v_min_u32_e32 v0, s13, v0
	v_mov_b32_e32 v149, s13
	v_cndmask_b32_e64 v0, v149, v0, s[52:53]
	v_cvt_f32_ubyte0_e32 v0, v0
	v_div_scale_f32 v149, s[16:17], v0, v0, 1.0
	v_rcp_f32_e32 v150, v149
	s_nop 0
	v_fma_f32 v151, -v149, v150, 1.0
	v_fmac_f32_e32 v150, v151, v150
	v_div_scale_f32 v151, vcc, 1.0, v0, 1.0
	v_mul_f32_e32 v152, v151, v150
	v_fma_f32 v153, -v149, v152, v151
	v_fmac_f32_e32 v152, v153, v150
	v_fma_f32 v149, -v149, v152, v151
	v_div_fmas_f32 v149, v149, v150, v152
	v_div_fixup_f32 v142, v149, v0, 1.0
	v_lshl_add_u32 v0, v121, 1, s7
	v_add_u32_e32 v0, 1, v0
	v_and_b32_e32 v0, 0x7ff, v0
	v_add_u32_e32 v0, 1, v0
	v_min_u32_e32 v0, s13, v0
	v_mov_b32_e32 v149, s13
	v_cndmask_b32_e64 v0, v149, v0, s[52:53]
	v_cvt_f32_ubyte0_e32 v0, v0
	v_div_scale_f32 v149, s[16:17], v0, v0, 1.0
	v_rcp_f32_e32 v150, v149
	s_nop 0
	v_fma_f32 v151, -v149, v150, 1.0
	v_fmac_f32_e32 v150, v151, v150
	v_div_scale_f32 v151, vcc, 1.0, v0, 1.0
	v_mul_f32_e32 v152, v151, v150
	v_fma_f32 v153, -v149, v152, v151
	v_fmac_f32_e32 v152, v153, v150
	v_fma_f32 v149, -v149, v152, v151
	v_div_fmas_f32 v149, v149, v150, v152
	v_div_fixup_f32 v143, v149, v0, 1.0
	v_cndmask_b32_e64 v0, v139, v140, s[52:53]
	v_mul_lo_u32 v0, v0, s19
	v_add_u32_e32 v86, v136, v0
	v_add_u32_e32 v87, v86, v118
	ds_read_b128 v[90:93], v87
	v_add_u32_e32 v87, v87, v119
	ds_read_b128 v[86:89], v87
	v_add_u32_e32 v149, v120, v0
	v_add_u32_e32 v149, v149, v118
	v_add_u32_e32 v141, 0x420, v149
	v_add_u32_e32 v149, 0xfffff7c0, v149
	v_add_u32_e32 v0, v149, v119
	s_lshr_b32 s15, s14, 1
	s_waitcnt lgkmcnt(0)
	v_mov_b64_e32 v[100:101], v[92:93]
	v_mov_b64_e32 v[98:99], v[90:91]
	v_mov_b64_e32 v[96:97], v[88:89]
	v_mov_b64_e32 v[94:95], v[86:87]
	s_cmp_eq_u32 s15, 0
	s_cbranch_scc1 .Lpw_tail_a
	ds_read_b128 v[150:153], v149 offset:1056
	ds_read_b128 v[154:157], v0 offset:1056
	ds_read_b128 v[158:161], v149
	ds_read_b128 v[252:255], v0
	v_add_u32_e32 v149, 0xfffff7c0, v149
	v_add_u32_e32 v0, 0xfffff7c0, v0
.Lpw_pair_a:
	s_add_i32 s15, s15, -1
	s_waitcnt lgkmcnt(2)
	v_pk_add_f32 v[100:101], v[100:101], v[152:153]
	v_pk_add_f32 v[98:99], v[98:99], v[150:151]
	v_pk_add_f32 v[96:97], v[96:97], v[156:157]
	v_pk_add_f32 v[94:95], v[94:95], v[154:155]
	ds_read_b128 v[150:153], v149 offset:1056
	ds_read_b128 v[154:157], v0 offset:1056
	s_cmp_lg_u32 s15, 0
	s_waitcnt lgkmcnt(2)
	v_pk_add_f32 v[100:101], v[100:101], v[160:161]
	v_pk_add_f32 v[98:99], v[98:99], v[158:159]
	v_pk_add_f32 v[96:97], v[96:97], v[254:255]
	v_pk_add_f32 v[94:95], v[94:95], v[252:253]
	s_cbranch_scc0 .Lpw_tail_b
	ds_read_b128 v[158:161], v149
	ds_read_b128 v[252:255], v0
	v_add_u32_e32 v149, 0xfffff7c0, v149
	v_add_u32_e32 v0, 0xfffff7c0, v0
	s_branch .Lpw_pair_a

; #define LAS __attribute__((address_space(3)))
; __device__ __forceinline__ unsigned pk2(float lo, float hi) { return f2bf(lo) | (f2bf(hi) << 16); }
; __device__ __forceinline__ void mix_phase(LAS unsigned char* lds, const Params& p, const int layer) {
;     ...
; #pragma unroll
;             for (int i = 0; i < 2; ++i) {
;                 const int rl = (tid >> 5) + 16 * i, bi = prt ? rl + 15 : (rl >> 3) * 23 + 15 + (rl & 7), t = (r0 + rl) & 2047;
;                 const LAS float* sp = SL + bi * 264 + q * 8;
;                 const f32x4 u0 = *(const LAS f32x4*)sp, u1 = *(const LAS f32x4*)(sp + 4);
;                 f32x4 s0 = u0, s1 = u1;
; #pragma unroll 4
;                 for (int j = 1; j < w; ++j) { s0 += *(const LAS f32x4*)(sp - j * 264); s1 += *(const LAS f32x4*)(sp - j * 264 + 4); }
;                 const int cnt = (prt && t + 1 < w) ? t + 1 : w; const float inv = 1.0f / (float)cnt;
;                 const f32x4 d0 = s0 * inv - u0, d1 = s1 * inv - u1;
;                 v4u o; o.x = pk2(d0[0], d0[1]); o.y = pk2(d0[2], d0[3]); o.z = pk2(d1[0], d1[1]); o.w = pk2(d1[2], d1[3]);
;                 *(LAS v4u*)(At + rl * 264 + q * 8) = o;
;             }
.Lpw_tail_b:
	v_add_u32_e32 v0, v141, v119
	ds_read_b128 v[158:161], v141
	ds_read_b128 v[252:255], v0
	s_waitcnt lgkmcnt(2)
	v_pk_add_f32 v[100:101], v[100:101], v[152:153]
	v_pk_add_f32 v[98:99], v[98:99], v[150:151]
	v_pk_add_f32 v[96:97], v[96:97], v[156:157]
	v_pk_add_f32 v[94:95], v[94:95], v[154:155]
	v_mov_b32_e32 v0, v142
	v_pk_fma_f32 v[90:91], v[0:1], v[98:99], v[90:91] op_sel_hi:[0,1,1] neg_lo:[0,0,1] neg_hi:[0,0,1]
	v_pk_fma_f32 v[92:93], v[0:1], v[100:101], v[92:93] op_sel_hi:[0,1,1] neg_lo:[0,0,1] neg_hi:[0,0,1]
	v_pk_fma_f32 v[86:87], v[0:1], v[94:95], v[86:87] op_sel_hi:[0,1,1] neg_lo:[0,0,1] neg_hi:[0,0,1]
	v_pk_fma_f32 v[88:89], v[0:1], v[96:97], v[88:89] op_sel_hi:[0,1,1] neg_lo:[0,0,1] neg_hi:[0,0,1]
	v_cvt_pk_bf16_f32 v90, v90, v91
	v_cvt_pk_bf16_f32 v91, v92, v93
	v_cvt_pk_bf16_f32 v92, v86, v87
	v_cvt_pk_bf16_f32 v93, v88, v89
	v_lshrrev_b32_e32 v0, 1, v118
	v_add_u32_e32 v149, v146, v0
	v_ashrrev_i32_e32 v0, 1, v119
	v_add_u32_e32 v0, v149, v0
	ds_write_b64 v149, v[90:91]
	ds_write_b64 v0, v[92:93]
	s_waitcnt lgkmcnt(2)
	v_pk_add_f32 v[98:99], v[98:99], v[158:159]
	v_pk_add_f32 v[100:101], v[100:101], v[160:161]
	v_pk_add_f32 v[94:95], v[94:95], v[252:253]
	v_pk_add_f32 v[96:97], v[96:97], v[254:255]
	v_pk_add_f32 v[98:99], v[98:99], v[150:151] neg_lo:[0,1] neg_hi:[0,1]
	v_pk_add_f32 v[100:101], v[100:101], v[152:153] neg_lo:[0,1] neg_hi:[0,1]
	v_pk_add_f32 v[94:95], v[94:95], v[154:155] neg_lo:[0,1] neg_hi:[0,1]
	v_pk_add_f32 v[96:97], v[96:97], v[156:157] neg_lo:[0,1] neg_hi:[0,1]
	v_mov_b32_e32 v0, v143
	v_pk_fma_f32 v[158:159], v[0:1], v[98:99], v[158:159] op_sel_hi:[0,1,1] neg_lo:[0,0,1] neg_hi:[0,0,1]
	v_pk_fma_f32 v[160:161], v[0:1], v[100:101], v[160:161] op_sel_hi:[0,1,1] neg_lo:[0,0,1] neg_hi:[0,0,1]
	v_pk_fma_f32 v[252:253], v[0:1], v[94:95], v[252:253] op_sel_hi:[0,1,1] neg_lo:[0,0,1] neg_hi:[0,0,1]
	v_pk_fma_f32 v[254:255], v[0:1], v[96:97], v[254:255] op_sel_hi:[0,1,1] neg_lo:[0,0,1] neg_hi:[0,0,1]
	v_cvt_pk_bf16_f32 v158, v158, v159
	v_cvt_pk_bf16_f32 v159, v160, v161
	v_cvt_pk_bf16_f32 v160, v252, v253
	v_cvt_pk_bf16_f32 v161, v254, v255
	v_lshrrev_b32_e32 v0, 1, v118
	v_add_u32_e32 v149, v147, v0
	v_ashrrev_i32_e32 v0, 1, v119
	v_add_u32_e32 v0, v149, v0
	ds_write_b64 v149, v[158:159]
	ds_write_b64 v0, v[160:161]
	s_waitcnt lgkmcnt(0)
	s_barrier
; #define LAS __attribute__((address_space(3)))
; __device__ __forceinline__ unsigned pk2(float lo, float hi) { return f2bf(lo) | (f2bf(hi) << 16); }
; __device__ __forceinline__ float bflo(unsigned w) { return __uint_as_float(w << 16); }
; __device__ __forceinline__ float bfhi(unsigned w) { return __uint_as_float(w & 0xffff0000u); }
; __device__ __forceinline__ void mix_phase(LAS unsigned char* lds, const Params& p, const int layer) {
;     ...
;             __syncthreads();
;             f32x4 acc[2][2];
; #pragma unroll
;             for (int m = 0; m < 2; ++m)
; #pragma unroll
;                 for (int n = 0; n < 2; ++n) acc[m][n] = (f32x4){0.f, 0.f, 0.f, 0.f};
; #pragma unroll
;             for (int ks = 0; ks < 8; ++ks) {
;                 bf16x8 a[2];
; #pragma unroll
;                 for (int m = 0; m < 2; ++m) a[m] = *(const LAS bf16x8*)(At + (m * 16 + fr) * 264 + ks * 32 + fq * 8);
; #pragma unroll
;                 for (int m = 0; m < 2; ++m)
; #pragma unroll
;                     for (int n = 0; n < 2; ++n) acc[m][n] = __builtin_amdgcn_mfma_f32_16x16x32_bf16(b[n][ks], a[m], acc[m][n], 0, 0, 0);
;             }
;             bf16* YA = (bf16*)(ws + WS_YA);
; #pragma unroll
;             for (int m = 0; m < 2; ++m)
; #pragma unroll
;                 for (int n = 0; n < 2; ++n) { const int r = r0 + m * 16 + fr, ch = g * 256 + wid * 32 + n * 16 + fq * 4; const v2u sg = sgc[m][n];
;                     const f32x4 y = acc[m][n] * ps[n] * (f32x4){bflo(sg.x), bfhi(sg.x), bflo(sg.y), bfhi(sg.y)};
;                     v2u o; o.x = pk2(y[0], y[1]); o.y = pk2(y[2], y[3]); *(v2u*)(YA + (size_t)r * KCAT + ch) = o; }
	ds_read_b128 v[86:89], v148
	ds_read_b128 v[90:93], v148 offset:8448
	ds_read_b128 v[150:153], v148 offset:64
	ds_read_b128 v[154:157], v148 offset:8512
	s_waitcnt lgkmcnt(0)
	s_waitcnt vmcnt(15)
	v_mfma_f32_16x16x32_bf16 v[94:97], v[42:45], v[86:89], 0
	v_or_b32_e32 v0, s7, v135
	s_movk_i32 s12, 0x1800
	s_and_b64 vcc, exec, s[90:91]
	v_mfma_f32_16x16x32_bf16 v[86:89], v[74:77], v[86:89], 0
	v_mfma_f32_16x16x32_bf16 v[98:101], v[42:45], v[90:93], 0
	v_mfma_f32_16x16x32_bf16 v[90:93], v[74:77], v[90:93], 0
	v_mfma_f32_16x16x32_bf16 v[94:97], v[38:41], v[150:153], v[94:97]
	v_mfma_f32_16x16x32_bf16 v[86:89], v[70:73], v[150:153], v[86:89]
	v_mfma_f32_16x16x32_bf16 v[98:101], v[38:41], v[154:157], v[98:101]
	v_mfma_f32_16x16x32_bf16 v[90:93], v[70:73], v[154:157], v[90:93]
	ds_read_b128 v[150:153], v148 offset:128
	ds_read_b128 v[154:157], v148 offset:8576
	s_waitcnt lgkmcnt(1)
	v_mfma_f32_16x16x32_bf16 v[94:97], v[34:37], v[150:153], v[94:97]
	v_mfma_f32_16x16x32_bf16 v[86:89], v[66:69], v[150:153], v[86:89]
	s_waitcnt lgkmcnt(0)
	v_mfma_f32_16x16x32_bf16 v[98:101], v[34:37], v[154:157], v[98:101]
	v_mfma_f32_16x16x32_bf16 v[90:93], v[66:69], v[154:157], v[90:93]
	ds_read_b128 v[150:153], v148 offset:192
	ds_read_b128 v[154:157], v148 offset:8640
	s_waitcnt lgkmcnt(1)
	v_mfma_f32_16x16x32_bf16 v[94:97], v[30:33], v[150:153], v[94:97]
	s_waitcnt vmcnt(10)
	v_mfma_f32_16x16x32_bf16 v[86:89], v[62:65], v[150:153], v[86:89]
	s_waitcnt lgkmcnt(0)
	v_mfma_f32_16x16x32_bf16 v[98:101], v[30:33], v[154:157], v[98:101]
	v_mfma_f32_16x16x32_bf16 v[90:93], v[62:65], v[154:157], v[90:93]
	ds_read_b128 v[150:153], v148 offset:256
	ds_read_b128 v[154:157], v148 offset:8704
	s_waitcnt lgkmcnt(1)
	v_mfma_f32_16x16x32_bf16 v[94:97], v[26:29], v[150:153], v[94:97]
	v_mfma_f32_16x16x32_bf16 v[86:89], v[58:61], v[150:153], v[86:89]
	s_waitcnt lgkmcnt(0)
	v_mfma_f32_16x16x32_bf16 v[98:101], v[26:29], v[154:157], v[98:101]
	v_mfma_f32_16x16x32_bf16 v[90:93], v[58:61], v[154:157], v[90:93]
	ds_read_b128 v[150:153], v148 offset:320
	ds_read_b128 v[154:157], v148 offset:8768
	s_waitcnt lgkmcnt(1)
	v_mfma_f32_16x16x32_bf16 v[94:97], v[22:25], v[150:153], v[94:97]
	v_mfma_f32_16x16x32_bf16 v[86:89], v[54:57], v[150:153], v[86:89]
	s_waitcnt lgkmcnt(0)
	v_mfma_f32_16x16x32_bf16 v[98:101], v[22:25], v[154:157], v[98:101]
	v_mfma_f32_16x16x32_bf16 v[90:93], v[54:57], v[154:157], v[90:93]
	ds_read_b128 v[150:153], v148 offset:384
	ds_read_b128 v[154:157], v148 offset:8832
	s_waitcnt lgkmcnt(1)
	v_mfma_f32_16x16x32_bf16 v[94:97], v[18:21], v[150:153], v[94:97]
	v_mfma_f32_16x16x32_bf16 v[86:89], v[50:53], v[150:153], v[86:89]
	s_waitcnt lgkmcnt(0)
	v_mfma_f32_16x16x32_bf16 v[98:101], v[18:21], v[154:157], v[98:101]
	v_mfma_f32_16x16x32_bf16 v[90:93], v[50:53], v[154:157], v[90:93]
	ds_read_b128 v[150:153], v148 offset:448
	ds_read_b128 v[154:157], v148 offset:8896
	s_waitcnt lgkmcnt(1)
	v_mfma_f32_16x16x32_bf16 v[94:97], v[14:17], v[150:153], v[94:97]
	s_waitcnt lgkmcnt(0)
	v_mfma_f32_16x16x32_bf16 v[98:101], v[14:17], v[154:157], v[98:101]
	s_nop 5
	v_mul_f32_e64 v94, v82, v94
	v_mul_f32_e64 v95, v83, v95
	v_pk_mul_f32 v[96:97], v[84:85], v[96:97]
	v_mfma_f32_16x16x32_bf16 v[90:93], v[46:49], v[154:157], v[90:93]
	s_waitcnt vmcnt(7)
	v_lshlrev_b32_e32 v156, 16, v108
	v_and_b32_e32 v157, 0xffff0000, v108
	v_lshlrev_b32_e32 v108, 16, v109
	v_and_b32_e32 v109, 0xffff0000, v109
	v_pk_mul_f32 v[94:95], v[94:95], v[156:157]
	v_pk_mul_f32 v[96:97], v[96:97], v[108:109]
	v_cvt_pk_bf16_f32 v94, v94, v95
	v_mfma_f32_16x16x32_bf16 v[86:89], v[46:49], v[150:153], v[86:89]
	v_add_u32_e32 v150, s6, v137
	v_mov_b64_e32 v[152:153], s[86:87]
	v_cvt_pk_bf16_f32 v95, v96, v97
	v_ashrrev_i32_e32 v151, 31, v150
	v_mad_i64_i32 v[154:155], s[6:7], v0, s12, v[152:153]
	v_lshlrev_b64 v[96:97], 1, v[150:151]
	v_lshl_add_u64 v[108:109], v[154:155], 0, v[96:97]
	global_store_dwordx2 v[108:109], v[94:95], off
	v_pk_mul_f32 v[86:87], v[78:79], v[86:87]
	s_waitcnt vmcnt(5)
	v_lshlrev_b32_e32 v94, 16, v106
	v_and_b32_e32 v95, 0xffff0000, v106
	v_pk_mul_f32 v[86:87], v[86:87], v[94:95]
	v_pk_mul_f32 v[88:89], v[80:81], v[88:89]
	v_lshlrev_b32_e32 v106, 16, v107
	v_and_b32_e32 v107, 0xffff0000, v107
	v_pk_mul_f32 v[88:89], v[88:89], v[106:107]
	v_cvt_pk_bf16_f32 v86, v86, v87
	v_cvt_pk_bf16_f32 v87, v88, v89
	v_pk_mul_f32 v[94:95], v[82:83], v[98:99]
	v_lshlrev_b32_e32 v98, 16, v104
	v_and_b32_e32 v99, 0xffff0000, v104
	v_or_b32_e32 v0, 16, v0
	v_pk_mul_f32 v[94:95], v[94:95], v[98:99]
	global_store_dwordx2 v[108:109], v[86:87], off offset:32
	v_mad_i64_i32 v[86:87], s[6:7], v0, s12, v[152:153]
	v_pk_mul_f32 v[88:89], v[84:85], v[100:101]
	v_lshlrev_b32_e32 v100, 16, v105
	v_and_b32_e32 v101, 0xffff0000, v105
	v_pk_mul_f32 v[88:89], v[88:89], v[100:101]
	v_cvt_pk_bf16_f32 v94, v94, v95
	v_cvt_pk_bf16_f32 v95, v88, v89
	v_pk_mul_f32 v[88:89], v[80:81], v[92:93]
	v_pk_mul_f32 v[90:91], v[78:79], v[90:91]
	v_lshlrev_b32_e32 v92, 16, v102
	v_and_b32_e32 v93, 0xffff0000, v102
	v_pk_mul_f32 v[90:91], v[90:91], v[92:93]
	v_lshl_add_u64 v[86:87], v[86:87], 0, v[96:97]
	global_store_dwordx2 v[86:87], v[94:95], off
	v_lshlrev_b32_e32 v94, 16, v103
	v_and_b32_e32 v95, 0xffff0000, v103
	v_pk_mul_f32 v[88:89], v[88:89], v[94:95]
	v_cvt_pk_bf16_f32 v90, v90, v91
	v_cvt_pk_bf16_f32 v91, v88, v89
	v_readlane_b32 s6, v249, 62
	s_add_i32 s2, s2, s6
	s_waitcnt vmcnt(4)
	v_mov_b64_e32 v[102:103], v[126:127]
	v_mov_b64_e32 v[104:105], v[124:125]
	s_waitcnt vmcnt(3)
	v_mov_b64_e32 v[106:107], v[128:129]
	v_mov_b64_e32 v[108:109], v[122:123]
	global_store_dwordx2 v[86:87], v[90:91], off offset:32
	s_cbranch_vccz .LBB0_551
